# Toeplitz k-loops (first half) software-pipelined one iteration deep
# baseline (speedup 1.0000x reference)
.LBB0_434:
	s_waitcnt lgkmcnt(0)
	s_lshl_b64 s[0:1], s[34:35], 18
	v_readlane_b32 s2, v253, 14
	s_add_u32 s0, s2, s0
	v_readlane_b32 s2, v253, 7
	s_addc_u32 s1, s2, s1
	v_lshlrev_b32_e32 v0, 8, v93
	v_lshl_add_u64 v[2:3], s[0:1], 0, v[0:1]
	v_mov_b32_e32 v91, v1
	v_ashrrev_i32_e32 v89, 31, v88
	v_lshl_add_u64 v[72:73], v[2:3], 0, v[90:91]
	v_lshlrev_b64 v[2:3], 12, v[88:89]
	v_lshl_add_u64 v[74:75], v[72:73], 0, v[2:3]
	s_mov_b64 s[0:1], 0x4000
	global_load_dwordx4 v[102:105], v[74:75], off offset:0
	global_load_dwordx4 v[106:109], v[74:75], off offset:64
	global_load_dwordx4 v[110:113], v[74:75], off offset:128
	global_load_dwordx4 v[114:117], v[74:75], off offset:192
	v_lshl_add_u64 v[74:75], v[74:75], 0, s[0:1]
	global_load_dwordx4 v[118:121], v[74:75], off offset:0
	global_load_dwordx4 v[122:125], v[74:75], off offset:64
	global_load_dwordx4 v[126:129], v[74:75], off offset:128
	global_load_dwordx4 v[130:133], v[74:75], off offset:192
	v_lshl_add_u64 v[74:75], v[74:75], 0, s[0:1]
	global_load_dwordx4 v[134:137], v[74:75], off offset:0
	global_load_dwordx4 v[138:141], v[74:75], off offset:64
	global_load_dwordx4 v[142:145], v[74:75], off offset:128
	global_load_dwordx4 v[146:149], v[74:75], off offset:192
	v_lshl_add_u64 v[74:75], v[74:75], 0, s[0:1]
	global_load_dwordx4 v[150:153], v[74:75], off offset:0
	global_load_dwordx4 v[154:157], v[74:75], off offset:64
	global_load_dwordx4 v[158:161], v[74:75], off offset:128
	global_load_dwordx4 v[162:165], v[74:75], off offset:192
	v_lshl_add_u64 v[74:75], v[74:75], 0, s[0:1]
	global_load_dwordx4 v[214:217], v[74:75], off offset:0
	global_load_dwordx4 v[218:221], v[74:75], off offset:64
	global_load_dwordx4 v[222:225], v[74:75], off offset:128
	global_load_dwordx4 v[226:229], v[74:75], off offset:192
	v_lshl_add_u64 v[74:75], v[74:75], 0, s[0:1]
	global_load_dwordx4 v[230:233], v[74:75], off offset:0
	global_load_dwordx4 v[234:237], v[74:75], off offset:64
	global_load_dwordx4 v[238:241], v[74:75], off offset:128
	global_load_dwordx4 v[242:245], v[74:75], off offset:192
	v_lshl_add_u64 v[74:75], v[74:75], 0, s[0:1]
	v_mul_u32_u24_e32 v0, 0xe0, v93
	v_add3_u32 v0, v95, v0, v90
	ds_read_b128 v[68:71], v0
	ds_read_b128 v[76:79], v0 offset:64
	ds_read_b128 v[80:83], v0 offset:128
	ds_read_b128 v[84:87], v0 offset:192
	v_readlane_b32 s2, v253, 36
	v_readlane_b32 s3, v253, 37
	s_lshl_b32 s98, s23, 4
	s_add_i32 s98, s98, s22
	s_mul_hi_i32 s99, s98, 0x120000
	s_mul_i32 s98, s98, 0x120000
	s_add_u32 s2, s2, s98
	s_addc_u32 s3, s3, s99
	v_add_u32_e32 v2, v100, v88
	v_ashrrev_i32_e32 v3, 31, v2
	v_lshlrev_b64 v[2:3], 6, v[2:3]
	v_lshl_add_u64 v[88:89], s[2:3], 0, v[90:91]
	v_lshl_add_u64 v[88:89], v[88:89], 0, v[2:3]
	s_waitcnt lgkmcnt(0)
	s_waitcnt vmcnt(20)
	v_mfma_f32_16x16x32_bf16 v[16:19], v[102:105], v[68:71], v[16:19]
	v_mfma_f32_16x16x32_bf16 v[16:19], v[106:109], v[76:79], v[16:19]
	v_mfma_f32_16x16x32_bf16 v[16:19], v[110:113], v[80:83], v[16:19]
	v_mfma_f32_16x16x32_bf16 v[16:19], v[114:117], v[84:87], v[16:19]
	global_load_dwordx4 v[102:105], v[74:75], off offset:0
	global_load_dwordx4 v[106:109], v[74:75], off offset:64
	global_load_dwordx4 v[110:113], v[74:75], off offset:128
	global_load_dwordx4 v[114:117], v[74:75], off offset:192
	v_lshl_add_u64 v[74:75], v[74:75], 0, s[0:1]
	s_waitcnt vmcnt(20)
	v_mfma_f32_16x16x32_bf16 v[12:15], v[118:121], v[68:71], v[12:15]
	v_mfma_f32_16x16x32_bf16 v[12:15], v[122:125], v[76:79], v[12:15]
	v_mfma_f32_16x16x32_bf16 v[12:15], v[126:129], v[80:83], v[12:15]
	v_mfma_f32_16x16x32_bf16 v[12:15], v[130:133], v[84:87], v[12:15]
	global_load_dwordx4 v[118:121], v[74:75], off offset:0
	global_load_dwordx4 v[122:125], v[74:75], off offset:64
	global_load_dwordx4 v[126:129], v[74:75], off offset:128
	global_load_dwordx4 v[130:133], v[74:75], off offset:192
	v_lshl_add_u64 v[74:75], v[74:75], 0, s[0:1]
	s_waitcnt vmcnt(20)
	v_mfma_f32_16x16x32_bf16 v[8:11], v[134:137], v[68:71], v[8:11]
	v_mfma_f32_16x16x32_bf16 v[8:11], v[138:141], v[76:79], v[8:11]
	v_mfma_f32_16x16x32_bf16 v[8:11], v[142:145], v[80:83], v[8:11]
	v_mfma_f32_16x16x32_bf16 v[8:11], v[146:149], v[84:87], v[8:11]
	global_load_dwordx4 v[134:137], v[74:75], off offset:0
	global_load_dwordx4 v[138:141], v[74:75], off offset:64
	global_load_dwordx4 v[142:145], v[74:75], off offset:128
	global_load_dwordx4 v[146:149], v[74:75], off offset:192
	v_lshl_add_u64 v[74:75], v[74:75], 0, s[0:1]
	s_waitcnt vmcnt(20)
	v_mfma_f32_16x16x32_bf16 v[4:7], v[150:153], v[68:71], v[4:7]
	v_mfma_f32_16x16x32_bf16 v[4:7], v[154:157], v[76:79], v[4:7]
	v_mfma_f32_16x16x32_bf16 v[4:7], v[158:161], v[80:83], v[4:7]
	v_mfma_f32_16x16x32_bf16 v[4:7], v[162:165], v[84:87], v[4:7]
	global_load_dwordx4 v[150:153], v[74:75], off offset:0
	global_load_dwordx4 v[154:157], v[74:75], off offset:64
	global_load_dwordx4 v[158:161], v[74:75], off offset:128
	global_load_dwordx4 v[162:165], v[74:75], off offset:192
	v_lshl_add_u64 v[74:75], v[74:75], 0, s[0:1]
	s_waitcnt vmcnt(20)
	v_mfma_f32_16x16x32_bf16 v[32:35], v[214:217], v[68:71], v[32:35]
	v_mfma_f32_16x16x32_bf16 v[32:35], v[218:221], v[76:79], v[32:35]
	v_mfma_f32_16x16x32_bf16 v[32:35], v[222:225], v[80:83], v[32:35]
	v_mfma_f32_16x16x32_bf16 v[32:35], v[226:229], v[84:87], v[32:35]
	global_load_dwordx4 v[214:217], v[74:75], off offset:0
	global_load_dwordx4 v[218:221], v[74:75], off offset:64
	global_load_dwordx4 v[222:225], v[74:75], off offset:128
	global_load_dwordx4 v[226:229], v[74:75], off offset:192
	v_lshl_add_u64 v[74:75], v[74:75], 0, s[0:1]
	s_waitcnt vmcnt(20)
	v_mfma_f32_16x16x32_bf16 v[28:31], v[230:233], v[68:71], v[28:31]
	v_mfma_f32_16x16x32_bf16 v[28:31], v[234:237], v[76:79], v[28:31]
	v_mfma_f32_16x16x32_bf16 v[28:31], v[238:241], v[80:83], v[28:31]
	v_mfma_f32_16x16x32_bf16 v[28:31], v[242:245], v[84:87], v[28:31]
	global_load_dwordx4 v[230:233], v[74:75], off offset:0
	global_load_dwordx4 v[234:237], v[74:75], off offset:64
	global_load_dwordx4 v[238:241], v[74:75], off offset:128
	global_load_dwordx4 v[242:245], v[74:75], off offset:192
	v_lshl_add_u64 v[74:75], v[74:75], 0, s[0:1]
	s_waitcnt vmcnt(20)
	v_mfma_f32_16x16x32_bf16 v[24:27], v[102:105], v[68:71], v[24:27]
	v_mfma_f32_16x16x32_bf16 v[24:27], v[106:109], v[76:79], v[24:27]
	v_mfma_f32_16x16x32_bf16 v[24:27], v[110:113], v[80:83], v[24:27]
	v_mfma_f32_16x16x32_bf16 v[24:27], v[114:117], v[84:87], v[24:27]
	global_load_dwordx4 v[102:105], v[74:75], off offset:0
	global_load_dwordx4 v[106:109], v[74:75], off offset:64
	global_load_dwordx4 v[110:113], v[74:75], off offset:128
	global_load_dwordx4 v[114:117], v[74:75], off offset:192
	v_lshl_add_u64 v[74:75], v[74:75], 0, s[0:1]
	s_waitcnt vmcnt(20)
	v_mfma_f32_16x16x32_bf16 v[20:23], v[118:121], v[68:71], v[20:23]
	v_mfma_f32_16x16x32_bf16 v[20:23], v[122:125], v[76:79], v[20:23]
	v_mfma_f32_16x16x32_bf16 v[20:23], v[126:129], v[80:83], v[20:23]
	v_mfma_f32_16x16x32_bf16 v[20:23], v[130:133], v[84:87], v[20:23]
	global_load_dwordx4 v[118:121], v[74:75], off offset:0
	global_load_dwordx4 v[122:125], v[74:75], off offset:64
	global_load_dwordx4 v[126:129], v[74:75], off offset:128
	global_load_dwordx4 v[130:133], v[74:75], off offset:192
	v_lshl_add_u64 v[74:75], v[74:75], 0, s[0:1]
	s_waitcnt vmcnt(20)
	v_mfma_f32_16x16x32_bf16 v[48:51], v[134:137], v[68:71], v[48:51]
	v_mfma_f32_16x16x32_bf16 v[48:51], v[138:141], v[76:79], v[48:51]
	v_mfma_f32_16x16x32_bf16 v[48:51], v[142:145], v[80:83], v[48:51]
	v_mfma_f32_16x16x32_bf16 v[48:51], v[146:149], v[84:87], v[48:51]
	global_load_dwordx4 v[134:137], v[74:75], off offset:0
	global_load_dwordx4 v[138:141], v[74:75], off offset:64
	global_load_dwordx4 v[142:145], v[74:75], off offset:128
	global_load_dwordx4 v[146:149], v[74:75], off offset:192
	v_lshl_add_u64 v[74:75], v[74:75], 0, s[0:1]
	s_waitcnt vmcnt(20)
	v_mfma_f32_16x16x32_bf16 v[44:47], v[150:153], v[68:71], v[44:47]
	v_mfma_f32_16x16x32_bf16 v[44:47], v[154:157], v[76:79], v[44:47]
	v_mfma_f32_16x16x32_bf16 v[44:47], v[158:161], v[80:83], v[44:47]
	v_mfma_f32_16x16x32_bf16 v[44:47], v[162:165], v[84:87], v[44:47]
	global_load_dwordx4 v[150:153], v[74:75], off offset:0
	global_load_dwordx4 v[154:157], v[74:75], off offset:64
	global_load_dwordx4 v[158:161], v[74:75], off offset:128
	global_load_dwordx4 v[162:165], v[74:75], off offset:192
	s_waitcnt vmcnt(20)
	v_mfma_f32_16x16x32_bf16 v[40:43], v[214:217], v[68:71], v[40:43]
	v_mfma_f32_16x16x32_bf16 v[40:43], v[218:221], v[76:79], v[40:43]
	v_mfma_f32_16x16x32_bf16 v[40:43], v[222:225], v[80:83], v[40:43]
	v_mfma_f32_16x16x32_bf16 v[40:43], v[226:229], v[84:87], v[40:43]
	s_waitcnt vmcnt(16)
	v_mfma_f32_16x16x32_bf16 v[36:39], v[230:233], v[68:71], v[36:39]
	v_mfma_f32_16x16x32_bf16 v[36:39], v[234:237], v[76:79], v[36:39]
	v_mfma_f32_16x16x32_bf16 v[36:39], v[238:241], v[80:83], v[36:39]
	v_mfma_f32_16x16x32_bf16 v[36:39], v[242:245], v[84:87], v[36:39]
	s_waitcnt vmcnt(12)
	v_mfma_f32_16x16x32_bf16 v[64:67], v[102:105], v[68:71], v[64:67]
	v_mfma_f32_16x16x32_bf16 v[64:67], v[106:109], v[76:79], v[64:67]
	v_mfma_f32_16x16x32_bf16 v[64:67], v[110:113], v[80:83], v[64:67]
	v_mfma_f32_16x16x32_bf16 v[64:67], v[114:117], v[84:87], v[64:67]
	s_waitcnt vmcnt(8)
	v_mfma_f32_16x16x32_bf16 v[60:63], v[118:121], v[68:71], v[60:63]
	v_mfma_f32_16x16x32_bf16 v[60:63], v[122:125], v[76:79], v[60:63]
	v_mfma_f32_16x16x32_bf16 v[60:63], v[126:129], v[80:83], v[60:63]
	v_mfma_f32_16x16x32_bf16 v[60:63], v[130:133], v[84:87], v[60:63]
	s_waitcnt vmcnt(4)
	v_mfma_f32_16x16x32_bf16 v[56:59], v[134:137], v[68:71], v[56:59]
	v_mfma_f32_16x16x32_bf16 v[56:59], v[138:141], v[76:79], v[56:59]
	v_mfma_f32_16x16x32_bf16 v[56:59], v[142:145], v[80:83], v[56:59]
	v_mfma_f32_16x16x32_bf16 v[56:59], v[146:149], v[84:87], v[56:59]
	s_waitcnt vmcnt(0)
	v_mfma_f32_16x16x32_bf16 v[52:55], v[150:153], v[68:71], v[52:55]
	v_mfma_f32_16x16x32_bf16 v[52:55], v[154:157], v[76:79], v[52:55]
	v_mfma_f32_16x16x32_bf16 v[52:55], v[158:161], v[80:83], v[52:55]
	v_mfma_f32_16x16x32_bf16 v[52:55], v[162:165], v[84:87], v[52:55]
	s_nop 7
	global_store_dwordx4 v[88:89], v[16:19], off
	global_store_dwordx4 v[88:89], v[12:15], off offset:256
	global_store_dwordx4 v[88:89], v[8:11], off offset:512
	global_store_dwordx4 v[88:89], v[4:7], off offset:768
	global_store_dwordx4 v[88:89], v[32:35], off offset:1024
	global_store_dwordx4 v[88:89], v[28:31], off offset:1280
	global_store_dwordx4 v[88:89], v[24:27], off offset:1536
	global_store_dwordx4 v[88:89], v[20:23], off offset:1792
	global_store_dwordx4 v[88:89], v[48:51], off offset:2048
	global_store_dwordx4 v[88:89], v[44:47], off offset:2304
	global_store_dwordx4 v[88:89], v[40:43], off offset:2560
	global_store_dwordx4 v[88:89], v[36:39], off offset:2816
	global_store_dwordx4 v[88:89], v[64:67], off offset:3072
	global_store_dwordx4 v[88:89], v[60:63], off offset:3328
	global_store_dwordx4 v[88:89], v[56:59], off offset:3584
	global_store_dwordx4 v[88:89], v[52:55], off offset:3840

.LBB0_721:
	ds_read_b128 v[214:217], v242 offset:4096
	ds_read_b128 v[218:221], v243 offset:4096
	ds_read_b128 v[222:225], v244 offset:4096
	ds_read_b128 v[226:229], v245 offset:4096
	ds_read_b128 v[162:165], v3
	v_add_u32_e32 v0, 2, v0
	v_add_u32_e32 v2, -2, v2
	v_add_u32_e32 v3, 64, v3
	v_add_u32_e32 v234, 12, v0
	v_cndmask_b32_e64 v230, v234, v2, vcc
	v_max_i32_e32 v242, 0, v230
	v_lshl_add_u32 v242, v242, 9, v89
	v_add_u32_e32 v235, 8, v0
	v_add_u32_e32 v239, 4, v2
	v_cndmask_b32_e64 v231, v235, v239, vcc
	v_max_i32_e32 v243, 0, v231
	v_lshl_add_u32 v243, v243, 9, v89
	v_add_u32_e32 v236, 4, v0
	v_add_u32_e32 v240, 8, v2
	v_cndmask_b32_e64 v232, v236, v240, vcc
	v_max_i32_e32 v244, 0, v232
	v_lshl_add_u32 v244, v244, 9, v89
	v_add_u32_e32 v241, 12, v2
	v_cndmask_b32_e64 v233, v0, v241, vcc
	v_max_i32_e32 v245, 0, v233
	v_lshl_add_u32 v245, v245, 9, v89
	v_cmp_lt_i32_e64 s[98:99], -1, v230
	v_cmp_lt_i32_e64 s[100:101], -1, v231
	v_cmp_lt_i32_e64 s[38:39], -1, v232
	v_cndmask_b32_e64 v242, v246, v242, s[98:99]
	v_cmp_lt_i32_e64 s[98:99], -1, v233
	v_cndmask_b32_e64 v243, v246, v243, s[100:101]
	v_cndmask_b32_e64 v244, v246, v244, s[38:39]
	s_nop 0
	v_cndmask_b32_e64 v245, v246, v245, s[98:99]
.Ltdb_721:
	ds_read_b128 v[142:145], v242 offset:4096
	ds_read_b128 v[146:149], v243 offset:4096
	ds_read_b128 v[150:153], v244 offset:4096
	ds_read_b128 v[154:157], v245 offset:4096
	ds_read_b128 v[158:161], v3
	v_add_u32_e32 v0, 2, v0
	v_add_u32_e32 v2, -2, v2
	v_add_u32_e32 v3, 64, v3
	v_add_u32_e32 v234, 12, v0
	v_cndmask_b32_e64 v230, v234, v2, vcc
	v_max_i32_e32 v242, 0, v230
	v_lshl_add_u32 v242, v242, 9, v89
	v_add_u32_e32 v235, 8, v0
	v_add_u32_e32 v239, 4, v2
	v_cndmask_b32_e64 v231, v235, v239, vcc
	v_max_i32_e32 v243, 0, v231
	v_lshl_add_u32 v243, v243, 9, v89
	v_add_u32_e32 v236, 4, v0
	v_add_u32_e32 v240, 8, v2
	v_cndmask_b32_e64 v232, v236, v240, vcc
	v_max_i32_e32 v244, 0, v232
	v_lshl_add_u32 v244, v244, 9, v89
	v_add_u32_e32 v241, 12, v2
	v_cndmask_b32_e64 v233, v0, v241, vcc
	v_max_i32_e32 v245, 0, v233
	v_lshl_add_u32 v245, v245, 9, v89
	v_cmp_lt_i32_e64 s[98:99], -1, v230
	v_cmp_lt_i32_e64 s[100:101], -1, v231
	v_cmp_lt_i32_e64 s[38:39], -1, v232
	v_cndmask_b32_e64 v242, v246, v242, s[98:99]
	v_cmp_lt_i32_e64 s[98:99], -1, v233
	v_cndmask_b32_e64 v243, v246, v243, s[100:101]
	v_cndmask_b32_e64 v244, v246, v244, s[38:39]
	s_nop 0
	v_cndmask_b32_e64 v245, v246, v245, s[98:99]
	s_add_i32 s33, s33, 1
	s_cmp_lt_i32 s33, s19
	s_waitcnt lgkmcnt(5)
	v_mfma_f32_16x16x32_bf16 v[16:19], v[214:217], v[162:165], v[16:19]
	v_mfma_f32_16x16x32_bf16 v[12:15], v[218:221], v[162:165], v[12:15]
	v_mfma_f32_16x16x32_bf16 v[8:11], v[222:225], v[162:165], v[8:11]
	v_mfma_f32_16x16x32_bf16 v[4:7], v[226:229], v[162:165], v[4:7]
	s_cbranch_scc0 .Ltdbx_721
	ds_read_b128 v[214:217], v242 offset:4096
	ds_read_b128 v[218:221], v243 offset:4096
	ds_read_b128 v[222:225], v244 offset:4096
	ds_read_b128 v[226:229], v245 offset:4096
	ds_read_b128 v[162:165], v3
	v_add_u32_e32 v0, 2, v0
	v_add_u32_e32 v2, -2, v2
	v_add_u32_e32 v3, 64, v3
	v_add_u32_e32 v234, 12, v0
	v_cndmask_b32_e64 v230, v234, v2, vcc
	v_max_i32_e32 v242, 0, v230
	v_lshl_add_u32 v242, v242, 9, v89
	v_add_u32_e32 v235, 8, v0
	v_add_u32_e32 v239, 4, v2
	v_cndmask_b32_e64 v231, v235, v239, vcc
	v_max_i32_e32 v243, 0, v231
	v_lshl_add_u32 v243, v243, 9, v89
	v_add_u32_e32 v236, 4, v0
	v_add_u32_e32 v240, 8, v2
	v_cndmask_b32_e64 v232, v236, v240, vcc
	v_max_i32_e32 v244, 0, v232
	v_lshl_add_u32 v244, v244, 9, v89
	v_add_u32_e32 v241, 12, v2
	v_cndmask_b32_e64 v233, v0, v241, vcc
	v_max_i32_e32 v245, 0, v233
	v_lshl_add_u32 v245, v245, 9, v89
	v_cmp_lt_i32_e64 s[98:99], -1, v230
	v_cmp_lt_i32_e64 s[100:101], -1, v231
	v_cmp_lt_i32_e64 s[38:39], -1, v232
	v_cndmask_b32_e64 v242, v246, v242, s[98:99]
	v_cmp_lt_i32_e64 s[98:99], -1, v233
	v_cndmask_b32_e64 v243, v246, v243, s[100:101]
	v_cndmask_b32_e64 v244, v246, v244, s[38:39]
	s_nop 0
	v_cndmask_b32_e64 v245, v246, v245, s[98:99]
	s_add_i32 s33, s33, 1
	s_cmp_lt_i32 s33, s19
	s_waitcnt lgkmcnt(5)
	v_mfma_f32_16x16x32_bf16 v[16:19], v[142:145], v[158:161], v[16:19]
	v_mfma_f32_16x16x32_bf16 v[12:15], v[146:149], v[158:161], v[12:15]
	v_mfma_f32_16x16x32_bf16 v[8:11], v[150:153], v[158:161], v[8:11]
	v_mfma_f32_16x16x32_bf16 v[4:7], v[154:157], v[158:161], v[4:7]
	s_cbranch_scc1 .Ltdb_721
.Ltdbx_721:
	s_branch .LBB0_723
.LBB0_722:
	v_mov_b32_e32 v2, v1
	v_mov_b32_e32 v3, v1
	v_mov_b32_e32 v0, v1
	v_mov_b64_e32 v[18:19], v[2:3]
	v_mov_b64_e32 v[14:15], v[2:3]
	v_mov_b64_e32 v[10:11], v[2:3]
	v_mov_b64_e32 v[6:7], v[2:3]
	v_mov_b64_e32 v[16:17], v[0:1]
	v_mov_b64_e32 v[12:13], v[0:1]
	v_mov_b64_e32 v[8:9], v[0:1]
	v_mov_b64_e32 v[4:5], v[0:1]

.LBB0_725:
	ds_read_b128 v[214:217], v242 offset:4096
	ds_read_b128 v[218:221], v243 offset:4096
	ds_read_b128 v[222:225], v244 offset:4096
	ds_read_b128 v[226:229], v245 offset:4096
	ds_read_b128 v[162:165], v3
	v_add_u32_e32 v0, 2, v0
	v_add_u32_e32 v2, -2, v2
	v_add_u32_e32 v3, 64, v3
	v_add_u32_e32 v234, 12, v0
	v_add_u32_e32 v238, -12, v2
	v_cndmask_b32_e64 v230, v234, v238, vcc
	v_max_i32_e32 v242, 0, v230
	v_lshl_add_u32 v242, v242, 9, v89
	v_add_u32_e32 v235, 8, v0
	v_add_u32_e32 v239, -8, v2
	v_cndmask_b32_e64 v231, v235, v239, vcc
	v_max_i32_e32 v243, 0, v231
	v_lshl_add_u32 v243, v243, 9, v89
	v_add_u32_e32 v236, 4, v0
	v_add_u32_e32 v240, -4, v2
	v_cndmask_b32_e64 v232, v236, v240, vcc
	v_max_i32_e32 v244, 0, v232
	v_lshl_add_u32 v244, v244, 9, v89
	v_cndmask_b32_e64 v233, v0, v2, vcc
	v_max_i32_e32 v245, 0, v233
	v_lshl_add_u32 v245, v245, 9, v89
	v_cmp_lt_i32_e64 s[98:99], -1, v230
	v_cmp_lt_i32_e64 s[100:101], -1, v231
	v_cmp_lt_i32_e64 s[38:39], -1, v232
	v_cndmask_b32_e64 v242, v246, v242, s[98:99]
	v_cmp_lt_i32_e64 s[98:99], -1, v233
	v_cndmask_b32_e64 v243, v246, v243, s[100:101]
	v_cndmask_b32_e64 v244, v246, v244, s[38:39]
	s_nop 0
	v_cndmask_b32_e64 v245, v246, v245, s[98:99]
.Ltdb_725:
	ds_read_b128 v[142:145], v242 offset:4096
	ds_read_b128 v[146:149], v243 offset:4096
	ds_read_b128 v[150:153], v244 offset:4096
	ds_read_b128 v[154:157], v245 offset:4096
	ds_read_b128 v[158:161], v3
	v_add_u32_e32 v0, 2, v0
	v_add_u32_e32 v2, -2, v2
	v_add_u32_e32 v3, 64, v3
	v_add_u32_e32 v234, 12, v0
	v_add_u32_e32 v238, -12, v2
	v_cndmask_b32_e64 v230, v234, v238, vcc
	v_max_i32_e32 v242, 0, v230
	v_lshl_add_u32 v242, v242, 9, v89
	v_add_u32_e32 v235, 8, v0
	v_add_u32_e32 v239, -8, v2
	v_cndmask_b32_e64 v231, v235, v239, vcc
	v_max_i32_e32 v243, 0, v231
	v_lshl_add_u32 v243, v243, 9, v89
	v_add_u32_e32 v236, 4, v0
	v_add_u32_e32 v240, -4, v2
	v_cndmask_b32_e64 v232, v236, v240, vcc
	v_max_i32_e32 v244, 0, v232
	v_lshl_add_u32 v244, v244, 9, v89
	v_cndmask_b32_e64 v233, v0, v2, vcc
	v_max_i32_e32 v245, 0, v233
	v_lshl_add_u32 v245, v245, 9, v89
	v_cmp_lt_i32_e64 s[98:99], -1, v230
	v_cmp_lt_i32_e64 s[100:101], -1, v231
	v_cmp_lt_i32_e64 s[38:39], -1, v232
	v_cndmask_b32_e64 v242, v246, v242, s[98:99]
	v_cmp_lt_i32_e64 s[98:99], -1, v233
	v_cndmask_b32_e64 v243, v246, v243, s[100:101]
	v_cndmask_b32_e64 v244, v246, v244, s[38:39]
	s_nop 0
	v_cndmask_b32_e64 v245, v246, v245, s[98:99]
	s_add_i32 s37, s37, 1
	s_cmp_lt_i32 s37, s36
	s_waitcnt lgkmcnt(5)
	v_mfma_f32_16x16x32_bf16 v[32:35], v[214:217], v[162:165], v[32:35]
	v_mfma_f32_16x16x32_bf16 v[28:31], v[218:221], v[162:165], v[28:31]
	v_mfma_f32_16x16x32_bf16 v[24:27], v[222:225], v[162:165], v[24:27]
	v_mfma_f32_16x16x32_bf16 v[20:23], v[226:229], v[162:165], v[20:23]
	s_cbranch_scc0 .Ltdbx_725
	ds_read_b128 v[214:217], v242 offset:4096
	ds_read_b128 v[218:221], v243 offset:4096
	ds_read_b128 v[222:225], v244 offset:4096
	ds_read_b128 v[226:229], v245 offset:4096
	ds_read_b128 v[162:165], v3
	v_add_u32_e32 v0, 2, v0
	v_add_u32_e32 v2, -2, v2
	v_add_u32_e32 v3, 64, v3
	v_add_u32_e32 v234, 12, v0
	v_add_u32_e32 v238, -12, v2
	v_cndmask_b32_e64 v230, v234, v238, vcc
	v_max_i32_e32 v242, 0, v230
	v_lshl_add_u32 v242, v242, 9, v89
	v_add_u32_e32 v235, 8, v0
	v_add_u32_e32 v239, -8, v2
	v_cndmask_b32_e64 v231, v235, v239, vcc
	v_max_i32_e32 v243, 0, v231
	v_lshl_add_u32 v243, v243, 9, v89
	v_add_u32_e32 v236, 4, v0
	v_add_u32_e32 v240, -4, v2
	v_cndmask_b32_e64 v232, v236, v240, vcc
	v_max_i32_e32 v244, 0, v232
	v_lshl_add_u32 v244, v244, 9, v89
	v_cndmask_b32_e64 v233, v0, v2, vcc
	v_max_i32_e32 v245, 0, v233
	v_lshl_add_u32 v245, v245, 9, v89
	v_cmp_lt_i32_e64 s[98:99], -1, v230
	v_cmp_lt_i32_e64 s[100:101], -1, v231
	v_cmp_lt_i32_e64 s[38:39], -1, v232
	v_cndmask_b32_e64 v242, v246, v242, s[98:99]
	v_cmp_lt_i32_e64 s[98:99], -1, v233
	v_cndmask_b32_e64 v243, v246, v243, s[100:101]
	v_cndmask_b32_e64 v244, v246, v244, s[38:39]
	s_nop 0
	v_cndmask_b32_e64 v245, v246, v245, s[98:99]
	s_add_i32 s37, s37, 1
	s_cmp_lt_i32 s37, s36
	s_waitcnt lgkmcnt(5)
	v_mfma_f32_16x16x32_bf16 v[32:35], v[142:145], v[158:161], v[32:35]
	v_mfma_f32_16x16x32_bf16 v[28:31], v[146:149], v[158:161], v[28:31]
	v_mfma_f32_16x16x32_bf16 v[24:27], v[150:153], v[158:161], v[24:27]
	v_mfma_f32_16x16x32_bf16 v[20:23], v[154:157], v[158:161], v[20:23]
	s_cbranch_scc1 .Ltdb_725
.Ltdbx_725:
	s_branch .LBB0_727
.LBB0_726:
	v_mov_b32_e32 v2, v1
	v_mov_b32_e32 v3, v1
	v_mov_b32_e32 v0, v1
	v_mov_b64_e32 v[34:35], v[2:3]
	v_mov_b64_e32 v[30:31], v[2:3]
	v_mov_b64_e32 v[26:27], v[2:3]
	v_mov_b64_e32 v[22:23], v[2:3]
	v_mov_b64_e32 v[32:33], v[0:1]
	v_mov_b64_e32 v[28:29], v[0:1]
	v_mov_b64_e32 v[24:25], v[0:1]
	v_mov_b64_e32 v[20:21], v[0:1]

.Ltdb_729:
	ds_read_b128 v[142:145], v242 offset:4096
	ds_read_b128 v[146:149], v243 offset:4096
	ds_read_b128 v[150:153], v244 offset:4096
	ds_read_b128 v[154:157], v245 offset:4096
	ds_read_b128 v[158:161], v3
	v_add_u32_e32 v0, 2, v0
	v_add_u32_e32 v2, -2, v2
	v_add_u32_e32 v3, 64, v3
	v_add_u32_e32 v234, 12, v0
	v_add_u32_e32 v238, -12, v2
	v_cndmask_b32_e64 v230, v234, v238, vcc
	v_max_i32_e32 v242, 0, v230
	v_lshl_add_u32 v242, v242, 9, v89
	v_add_u32_e32 v235, 8, v0
	v_add_u32_e32 v239, -8, v2
	v_cndmask_b32_e64 v231, v235, v239, vcc
	v_max_i32_e32 v243, 0, v231
	v_lshl_add_u32 v243, v243, 9, v89
	v_add_u32_e32 v236, 4, v0
	v_add_u32_e32 v240, -4, v2
	v_cndmask_b32_e64 v232, v236, v240, vcc
	v_max_i32_e32 v244, 0, v232
	v_lshl_add_u32 v244, v244, 9, v89
	v_cndmask_b32_e64 v233, v0, v2, vcc
	v_max_i32_e32 v245, 0, v233
	v_lshl_add_u32 v245, v245, 9, v89
	v_cmp_lt_i32_e64 s[98:99], -1, v230
	v_cmp_lt_i32_e64 s[100:101], -1, v231
	v_cmp_lt_i32_e64 s[38:39], -1, v232
	v_cndmask_b32_e64 v242, v246, v242, s[98:99]
	v_cmp_lt_i32_e64 s[98:99], -1, v233
	v_cndmask_b32_e64 v243, v246, v243, s[100:101]
	v_cndmask_b32_e64 v244, v246, v244, s[38:39]
	s_nop 0
	v_cndmask_b32_e64 v245, v246, v245, s[98:99]
	s_add_i32 s42, s42, 1
	s_cmp_lt_i32 s42, s40
	s_waitcnt lgkmcnt(5)
	v_mfma_f32_16x16x32_bf16 v[48:51], v[214:217], v[162:165], v[48:51]
	v_mfma_f32_16x16x32_bf16 v[44:47], v[218:221], v[162:165], v[44:47]
	v_mfma_f32_16x16x32_bf16 v[40:43], v[222:225], v[162:165], v[40:43]
	v_mfma_f32_16x16x32_bf16 v[36:39], v[226:229], v[162:165], v[36:39]
	s_cbranch_scc0 .Ltdbx_729
	ds_read_b128 v[214:217], v242 offset:4096
	ds_read_b128 v[218:221], v243 offset:4096
	ds_read_b128 v[222:225], v244 offset:4096
	ds_read_b128 v[226:229], v245 offset:4096
	ds_read_b128 v[162:165], v3
	v_add_u32_e32 v0, 2, v0
	v_add_u32_e32 v2, -2, v2
	v_add_u32_e32 v3, 64, v3
	v_add_u32_e32 v234, 12, v0
	v_add_u32_e32 v238, -12, v2
	v_cndmask_b32_e64 v230, v234, v238, vcc
	v_max_i32_e32 v242, 0, v230
	v_lshl_add_u32 v242, v242, 9, v89
	v_add_u32_e32 v235, 8, v0
	v_add_u32_e32 v239, -8, v2
	v_cndmask_b32_e64 v231, v235, v239, vcc
	v_max_i32_e32 v243, 0, v231
	v_lshl_add_u32 v243, v243, 9, v89
	v_add_u32_e32 v236, 4, v0
	v_add_u32_e32 v240, -4, v2
	v_cndmask_b32_e64 v232, v236, v240, vcc
	v_max_i32_e32 v244, 0, v232
	v_lshl_add_u32 v244, v244, 9, v89
	v_cndmask_b32_e64 v233, v0, v2, vcc
	v_max_i32_e32 v245, 0, v233
	v_lshl_add_u32 v245, v245, 9, v89
	v_cmp_lt_i32_e64 s[98:99], -1, v230
	v_cmp_lt_i32_e64 s[100:101], -1, v231
	v_cmp_lt_i32_e64 s[38:39], -1, v232
	v_cndmask_b32_e64 v242, v246, v242, s[98:99]
	v_cmp_lt_i32_e64 s[98:99], -1, v233
	v_cndmask_b32_e64 v243, v246, v243, s[100:101]
	v_cndmask_b32_e64 v244, v246, v244, s[38:39]
	s_nop 0
	v_cndmask_b32_e64 v245, v246, v245, s[98:99]
	s_add_i32 s42, s42, 1
	s_cmp_lt_i32 s42, s40
	s_waitcnt lgkmcnt(5)
	v_mfma_f32_16x16x32_bf16 v[48:51], v[142:145], v[158:161], v[48:51]
	v_mfma_f32_16x16x32_bf16 v[44:47], v[146:149], v[158:161], v[44:47]
	v_mfma_f32_16x16x32_bf16 v[40:43], v[150:153], v[158:161], v[40:43]
	v_mfma_f32_16x16x32_bf16 v[36:39], v[154:157], v[158:161], v[36:39]
	s_cbranch_scc1 .Ltdb_729
.Ltdbx_729:
	s_branch .LBB0_731
.LBB0_730:
	v_mov_b32_e32 v2, v1
	v_mov_b32_e32 v3, v1
	v_mov_b32_e32 v0, v1
	v_mov_b64_e32 v[50:51], v[2:3]
	v_mov_b64_e32 v[46:47], v[2:3]
	v_mov_b64_e32 v[42:43], v[2:3]
	v_mov_b64_e32 v[38:39], v[2:3]
	v_mov_b64_e32 v[48:49], v[0:1]
	v_mov_b64_e32 v[44:45], v[0:1]
	v_mov_b64_e32 v[40:41], v[0:1]
	v_mov_b64_e32 v[36:37], v[0:1]

.Ltdb_733:
	ds_read_b128 v[142:145], v242 offset:4096
	ds_read_b128 v[146:149], v243 offset:4096
	ds_read_b128 v[150:153], v244 offset:4096
	ds_read_b128 v[154:157], v245 offset:4096
	ds_read_b128 v[158:161], v3
	v_add_u32_e32 v0, 2, v0
	v_add_u32_e32 v2, -2, v2
	v_add_u32_e32 v3, 64, v3
	v_add_u32_e32 v234, 12, v0
	v_add_u32_e32 v238, -12, v2
	v_cndmask_b32_e64 v230, v234, v238, vcc
	v_max_i32_e32 v242, 0, v230
	v_lshl_add_u32 v242, v242, 9, v89
	v_add_u32_e32 v235, 8, v0
	v_add_u32_e32 v239, -8, v2
	v_cndmask_b32_e64 v231, v235, v239, vcc
	v_max_i32_e32 v243, 0, v231
	v_lshl_add_u32 v243, v243, 9, v89
	v_add_u32_e32 v236, 4, v0
	v_add_u32_e32 v240, -4, v2
	v_cndmask_b32_e64 v232, v236, v240, vcc
	v_max_i32_e32 v244, 0, v232
	v_lshl_add_u32 v244, v244, 9, v89
	v_cndmask_b32_e64 v233, v0, v2, vcc
	v_max_i32_e32 v245, 0, v233
	v_lshl_add_u32 v245, v245, 9, v89
	v_cmp_lt_i32_e64 s[98:99], -1, v230
	v_cmp_lt_i32_e64 s[100:101], -1, v231
	v_cmp_lt_i32_e64 s[38:39], -1, v232
	v_cndmask_b32_e64 v242, v246, v242, s[98:99]
	v_cmp_lt_i32_e64 s[98:99], -1, v233
	v_cndmask_b32_e64 v243, v246, v243, s[100:101]
	v_cndmask_b32_e64 v244, v246, v244, s[38:39]
	s_nop 0
	v_cndmask_b32_e64 v245, v246, v245, s[98:99]
	s_add_i32 s43, s43, 1
	s_cmp_lt_i32 s43, s42
	s_waitcnt lgkmcnt(5)
	v_mfma_f32_16x16x32_bf16 v[80:83], v[214:217], v[162:165], v[80:83]
	v_mfma_f32_16x16x32_bf16 v[76:79], v[218:221], v[162:165], v[76:79]
	v_mfma_f32_16x16x32_bf16 v[72:75], v[222:225], v[162:165], v[72:75]
	v_mfma_f32_16x16x32_bf16 v[68:71], v[226:229], v[162:165], v[68:71]
	s_cbranch_scc0 .Ltdbx_733
	ds_read_b128 v[214:217], v242 offset:4096
	ds_read_b128 v[218:221], v243 offset:4096
	ds_read_b128 v[222:225], v244 offset:4096
	ds_read_b128 v[226:229], v245 offset:4096
	ds_read_b128 v[162:165], v3
	v_add_u32_e32 v0, 2, v0
	v_add_u32_e32 v2, -2, v2
	v_add_u32_e32 v3, 64, v3
	v_add_u32_e32 v234, 12, v0
	v_add_u32_e32 v238, -12, v2
	v_cndmask_b32_e64 v230, v234, v238, vcc
	v_max_i32_e32 v242, 0, v230
	v_lshl_add_u32 v242, v242, 9, v89
	v_add_u32_e32 v235, 8, v0
	v_add_u32_e32 v239, -8, v2
	v_cndmask_b32_e64 v231, v235, v239, vcc
	v_max_i32_e32 v243, 0, v231
	v_lshl_add_u32 v243, v243, 9, v89
	v_add_u32_e32 v236, 4, v0
	v_add_u32_e32 v240, -4, v2
	v_cndmask_b32_e64 v232, v236, v240, vcc
	v_max_i32_e32 v244, 0, v232
	v_lshl_add_u32 v244, v244, 9, v89
	v_cndmask_b32_e64 v233, v0, v2, vcc
	v_max_i32_e32 v245, 0, v233
	v_lshl_add_u32 v245, v245, 9, v89
	v_cmp_lt_i32_e64 s[98:99], -1, v230
	v_cmp_lt_i32_e64 s[100:101], -1, v231
	v_cmp_lt_i32_e64 s[38:39], -1, v232
	v_cndmask_b32_e64 v242, v246, v242, s[98:99]
	v_cmp_lt_i32_e64 s[98:99], -1, v233
	v_cndmask_b32_e64 v243, v246, v243, s[100:101]
	v_cndmask_b32_e64 v244, v246, v244, s[38:39]
	s_nop 0
	v_cndmask_b32_e64 v245, v246, v245, s[98:99]
	s_add_i32 s43, s43, 1
	s_cmp_lt_i32 s43, s42
	s_waitcnt lgkmcnt(5)
	v_mfma_f32_16x16x32_bf16 v[80:83], v[142:145], v[158:161], v[80:83]
	v_mfma_f32_16x16x32_bf16 v[76:79], v[146:149], v[158:161], v[76:79]
	v_mfma_f32_16x16x32_bf16 v[72:75], v[150:153], v[158:161], v[72:75]
	v_mfma_f32_16x16x32_bf16 v[68:71], v[154:157], v[158:161], v[68:71]
	s_cbranch_scc1 .Ltdb_733
.Ltdbx_733:
	s_branch .LBB0_735
.LBB0_734:
	v_mov_b32_e32 v2, v1
	v_mov_b32_e32 v3, v1
	v_mov_b32_e32 v0, v1
	v_mov_b64_e32 v[70:71], v[2:3]
	v_mov_b64_e32 v[74:75], v[2:3]
	v_mov_b64_e32 v[78:79], v[2:3]
	v_mov_b64_e32 v[82:83], v[2:3]
	v_mov_b64_e32 v[68:69], v[0:1]
	v_mov_b64_e32 v[72:73], v[0:1]
	v_mov_b64_e32 v[76:77], v[0:1]
	v_mov_b64_e32 v[80:81], v[0:1]
